# k13 + XQ (both layers) and MLA Q up-projection epilogues: per-row rstd via LDS table
# speedup vs baseline: 1.0352x; 1.0052x over previous
; __device__ __forceinline__ unsigned cvtpk(float lo, float hi) { f32x2_t v = {lo, hi}; bf16x2_t b = __builtin_convertvector(v, bf16x2_t); return __builtin_bit_cast(unsigned, b); }
; __device__ __forceinline__ float ssq_sum(const float* p) {
;     const f32x4 a = *(const f32x4*)p, b = *(const f32x4*)(p + 4), c = *(const f32x4*)(p + 8), d = *(const f32x4*)(p + 12);
;     return (((a[0] + a[1]) + (a[2] + a[3])) + ((b[0] + b[1]) + (b[2] + b[3]))) + (((c[0] + c[1]) + (c[2] + c[3])) + ((d[0] + d[1]) + (d[2] + d[3])));
;     __device__ __forceinline__ void operator()(const f32x4 (&acc)[2][2][4][2], const Unit& u, int wr, int wc, int fr, int fq) const {
;         const int row0 = u.pm * BM + wr * 64 + fr, col0 = u.pn * BM + wc * 32 + 8 * fq;
;         float* so = (u.pn == 0) ? ssq_o[0] : (u.pn == 1) ? ssq_o[1] : (u.pn == 2) ? ssq_o[2] : (u.pn == 3) ? ssq_o[3] : nullptr;
; #pragma unroll
;         for (int ai = 0; ai < 2; ++ai)
; #pragma unroll
;             for (int m = 0; m < 4; ++m) {
;                 const int row = row0 + ai * HALF + m * 16; float s = 0.f;
;                 const float rs = ssq_in ? 1.0f / sqrtf(ssq_sum(ssq_in + (size_t)row * 16) * inv_dim + EPS) : 1.0f;
; #pragma unroll
;                 for (int bj = 0; bj < 2; ++bj) {
;                     int col = col0 + bj * HALF; if (hd_in) col = (col / hd_in) * hd_out + (col % hd_in);
;                     const f32x4 v0 = acc[ai][bj][m][0] * rs, v1 = acc[ai][bj][m][1] * rs;
;                     u32x4 w; w.x = cvtpk(v0[0], v0[1]); w.y = cvtpk(v0[2], v0[3]); w.z = cvtpk(v1[0], v1[1]); w.w = cvtpk(v1[2], v1[3]);
;                     *(u32x4*)(O + (size_t)row * ldc + col) = w;
.LBB0_814:
	v_readlane_b32 vcc_lo, v254, 7
	v_mbcnt_lo_u32_b32 v156, -1, 0
	v_mbcnt_hi_u32_b32 v156, -1, v156
	v_lshrrev_b32_e32 v157, 1, v156
	v_lshl_add_u32 v157, vcc_lo, 5, v157
	v_and_b32_e32 v158, 1, v156
	v_lshl_add_u32 v159, s8, 8, v157
	v_lshlrev_b32_e32 v159, 6, v159
	v_lshl_add_u32 v159, v158, 5, v159
	global_load_dwordx4 v[160:163], v159, s[16:17]
	global_load_dwordx4 v[164:167], v159, s[16:17] offset:16
	v_lshl_add_u32 v168, s8, 8, v148
	v_mul_u32_u24_e32 v168, 0x400, v168
	v_lshl_or_b32 v169, s9, 8, v150
	v_lshl_add_u32 v168, v169, 1, v168
	v_lshlrev_b32_e32 v157, 2, v157
	v_add_u32_e32 v157, 0x20100, v157
	v_lshlrev_b32_e32 v158, 2, v148
	v_add_u32_e32 v158, 0x20100, v158
	s_waitcnt vmcnt(0)
	v_pk_add_f32 v[160:161], v[160:161], v[162:163]
	v_pk_add_f32 v[164:165], v[164:165], v[166:167]
	v_pk_add_f32 v[160:161], v[160:161], v[164:165]
	v_add_f32_e32 v160, v160, v161
	s_nop 1
	v_add_f32_dpp v160, v160, v160 quad_perm:[1,0,3,2] row_mask:0xf bank_mask:0xf
	v_fmamk_f32 v160, v160, 0x3a800000, v154
	v_rsq_f32_e32 v160, v160
	s_nop 0
	ds_write_b32 v157, v160
	s_waitcnt lgkmcnt(0)
	s_barrier
	ds_read_b32 v160, v158 offset:0
	ds_read_b32 v161, v158 offset:64
	ds_read_b32 v162, v158 offset:128
	ds_read_b32 v163, v158 offset:192
	ds_read_b32 v164, v158 offset:512
	ds_read_b32 v165, v158 offset:576
	ds_read_b32 v166, v158 offset:640
	ds_read_b32 v167, v158 offset:704
	s_waitcnt lgkmcnt(7)
	v_mul_f32_e32 v124, v160, v124
	v_mul_f32_e32 v125, v160, v125
	v_mul_f32_e32 v126, v160, v126
	v_mul_f32_e32 v127, v160, v127
	v_mul_f32_e32 v120, v160, v120
	v_mul_f32_e32 v121, v160, v121
	v_mul_f32_e32 v122, v160, v122
	v_mul_f32_e32 v123, v160, v123
	v_mul_f32_e32 v116, v160, v116
	v_mul_f32_e32 v117, v160, v117
	v_mul_f32_e32 v118, v160, v118
	v_mul_f32_e32 v119, v160, v119
	v_mul_f32_e32 v112, v160, v112
	v_mul_f32_e32 v113, v160, v113
	v_mul_f32_e32 v114, v160, v114
	v_mul_f32_e32 v115, v160, v115
	v_cvt_pk_bf16_f32 v124, v124, v125
	v_cvt_pk_bf16_f32 v125, v126, v127
	v_cvt_pk_bf16_f32 v126, v120, v121
	v_cvt_pk_bf16_f32 v127, v122, v123
	v_cvt_pk_bf16_f32 v116, v116, v117
	v_cvt_pk_bf16_f32 v117, v118, v119
	v_cvt_pk_bf16_f32 v118, v112, v113
	v_cvt_pk_bf16_f32 v119, v114, v115
	global_store_dwordx4 v168, v[124:127], s[14:15]
	global_store_dwordx4 v168, v[116:119], s[14:15] offset:256
	s_waitcnt lgkmcnt(6)
	v_mul_f32_e32 v108, v161, v108
	v_mul_f32_e32 v109, v161, v109
	v_mul_f32_e32 v110, v161, v110
	v_mul_f32_e32 v111, v161, v111
	v_mul_f32_e32 v104, v161, v104
	v_mul_f32_e32 v105, v161, v105
	v_mul_f32_e32 v106, v161, v106
	v_mul_f32_e32 v107, v161, v107
	v_mul_f32_e32 v100, v161, v100
	v_mul_f32_e32 v101, v161, v101
	v_mul_f32_e32 v102, v161, v102
	v_mul_f32_e32 v103, v161, v103
	v_mul_f32_e32 v96, v161, v96
	v_mul_f32_e32 v97, v161, v97
	v_mul_f32_e32 v98, v161, v98
	v_mul_f32_e32 v99, v161, v99
	v_cvt_pk_bf16_f32 v108, v108, v109
	v_cvt_pk_bf16_f32 v109, v110, v111
	v_cvt_pk_bf16_f32 v110, v104, v105
	v_cvt_pk_bf16_f32 v111, v106, v107
	v_cvt_pk_bf16_f32 v100, v100, v101
	v_cvt_pk_bf16_f32 v101, v102, v103
	v_cvt_pk_bf16_f32 v102, v96, v97
	v_cvt_pk_bf16_f32 v103, v98, v99
	v_add_u32_e32 v169, 0x4000, v168
	global_store_dwordx4 v169, v[108:111], s[14:15]
	global_store_dwordx4 v169, v[100:103], s[14:15] offset:256
	s_waitcnt lgkmcnt(5)
	v_mul_f32_e32 v92, v162, v92
	v_mul_f32_e32 v93, v162, v93
	v_mul_f32_e32 v94, v162, v94
	v_mul_f32_e32 v95, v162, v95
	v_mul_f32_e32 v88, v162, v88
	v_mul_f32_e32 v89, v162, v89
	v_mul_f32_e32 v90, v162, v90
	v_mul_f32_e32 v91, v162, v91
	v_mul_f32_e32 v84, v162, v84
	v_mul_f32_e32 v85, v162, v85
	v_mul_f32_e32 v86, v162, v86
	v_mul_f32_e32 v87, v162, v87
	v_mul_f32_e32 v80, v162, v80
	v_mul_f32_e32 v81, v162, v81
	v_mul_f32_e32 v82, v162, v82
	v_mul_f32_e32 v83, v162, v83
	v_cvt_pk_bf16_f32 v92, v92, v93
	v_cvt_pk_bf16_f32 v93, v94, v95
	v_cvt_pk_bf16_f32 v94, v88, v89
	v_cvt_pk_bf16_f32 v95, v90, v91
	v_cvt_pk_bf16_f32 v84, v84, v85
	v_cvt_pk_bf16_f32 v85, v86, v87
	v_cvt_pk_bf16_f32 v86, v80, v81
	v_cvt_pk_bf16_f32 v87, v82, v83
	v_add_u32_e32 v169, 0x8000, v168
	global_store_dwordx4 v169, v[92:95], s[14:15]
	global_store_dwordx4 v169, v[84:87], s[14:15] offset:256
	s_waitcnt lgkmcnt(4)
; __device__ __forceinline__ unsigned cvtpk(float lo, float hi) { f32x2_t v = {lo, hi}; bf16x2_t b = __builtin_convertvector(v, bf16x2_t); return __builtin_bit_cast(unsigned, b); }
;     __device__ __forceinline__ void operator()(const f32x4 (&acc)[2][2][4][2], const Unit& u, int wr, int wc, int fr, int fq) const {
;     ...
;             for (int m = 0; m < 4; ++m) {
;                 const int row = row0 + ai * HALF + m * 16; float s = 0.f;
;                 const float rs = ssq_in ? 1.0f / sqrtf(ssq_sum(ssq_in + (size_t)row * 16) * inv_dim + EPS) : 1.0f;
; #pragma unroll
;                 for (int bj = 0; bj < 2; ++bj) {
;                     int col = col0 + bj * HALF; if (hd_in) col = (col / hd_in) * hd_out + (col % hd_in);
;                     const f32x4 v0 = acc[ai][bj][m][0] * rs, v1 = acc[ai][bj][m][1] * rs;
;                     u32x4 w; w.x = cvtpk(v0[0], v0[1]); w.y = cvtpk(v0[2], v0[3]); w.z = cvtpk(v1[0], v1[1]); w.w = cvtpk(v1[2], v1[3]);
;                     *(u32x4*)(O + (size_t)row * ldc + col) = w;
	v_mul_f32_e32 v76, v163, v76
	v_mul_f32_e32 v77, v163, v77
	v_mul_f32_e32 v78, v163, v78
	v_mul_f32_e32 v79, v163, v79
	v_mul_f32_e32 v72, v163, v72
	v_mul_f32_e32 v73, v163, v73
	v_mul_f32_e32 v74, v163, v74
	v_mul_f32_e32 v75, v163, v75
	v_mul_f32_e32 v68, v163, v68
	v_mul_f32_e32 v69, v163, v69
	v_mul_f32_e32 v70, v163, v70
	v_mul_f32_e32 v71, v163, v71
	v_mul_f32_e32 v64, v163, v64
	v_mul_f32_e32 v65, v163, v65
	v_mul_f32_e32 v66, v163, v66
	v_mul_f32_e32 v67, v163, v67
	v_cvt_pk_bf16_f32 v76, v76, v77
	v_cvt_pk_bf16_f32 v77, v78, v79
	v_cvt_pk_bf16_f32 v78, v72, v73
	v_cvt_pk_bf16_f32 v79, v74, v75
	v_cvt_pk_bf16_f32 v68, v68, v69
	v_cvt_pk_bf16_f32 v69, v70, v71
	v_cvt_pk_bf16_f32 v70, v64, v65
	v_cvt_pk_bf16_f32 v71, v66, v67
	v_add_u32_e32 v169, 0xc000, v168
	global_store_dwordx4 v169, v[76:79], s[14:15]
	global_store_dwordx4 v169, v[68:71], s[14:15] offset:256
	s_waitcnt lgkmcnt(3)
	v_mul_f32_e32 v60, v164, v60
	v_mul_f32_e32 v61, v164, v61
	v_mul_f32_e32 v62, v164, v62
	v_mul_f32_e32 v63, v164, v63
	v_mul_f32_e32 v56, v164, v56
	v_mul_f32_e32 v57, v164, v57
	v_mul_f32_e32 v58, v164, v58
	v_mul_f32_e32 v59, v164, v59
	v_mul_f32_e32 v52, v164, v52
	v_mul_f32_e32 v53, v164, v53
	v_mul_f32_e32 v54, v164, v54
	v_mul_f32_e32 v55, v164, v55
	v_mul_f32_e32 v48, v164, v48
	v_mul_f32_e32 v49, v164, v49
	v_mul_f32_e32 v50, v164, v50
	v_mul_f32_e32 v51, v164, v51
	v_cvt_pk_bf16_f32 v60, v60, v61
	v_cvt_pk_bf16_f32 v61, v62, v63
	v_cvt_pk_bf16_f32 v62, v56, v57
	v_cvt_pk_bf16_f32 v63, v58, v59
	v_cvt_pk_bf16_f32 v52, v52, v53
	v_cvt_pk_bf16_f32 v53, v54, v55
	v_cvt_pk_bf16_f32 v54, v48, v49
	v_cvt_pk_bf16_f32 v55, v50, v51
	v_add_u32_e32 v169, 0x20000, v168
	global_store_dwordx4 v169, v[60:63], s[14:15]
	global_store_dwordx4 v169, v[52:55], s[14:15] offset:256
	s_waitcnt lgkmcnt(2)
	v_mul_f32_e32 v44, v165, v44
	v_mul_f32_e32 v45, v165, v45
	v_mul_f32_e32 v46, v165, v46
	v_mul_f32_e32 v47, v165, v47
	v_mul_f32_e32 v40, v165, v40
	v_mul_f32_e32 v41, v165, v41
	v_mul_f32_e32 v42, v165, v42
	v_mul_f32_e32 v43, v165, v43
	v_mul_f32_e32 v36, v165, v36
	v_mul_f32_e32 v37, v165, v37
	v_mul_f32_e32 v38, v165, v38
	v_mul_f32_e32 v39, v165, v39
	v_mul_f32_e32 v32, v165, v32
	v_mul_f32_e32 v33, v165, v33
	v_mul_f32_e32 v34, v165, v34
	v_mul_f32_e32 v35, v165, v35
	v_cvt_pk_bf16_f32 v44, v44, v45
	v_cvt_pk_bf16_f32 v45, v46, v47
	v_cvt_pk_bf16_f32 v46, v40, v41
	v_cvt_pk_bf16_f32 v47, v42, v43
	v_cvt_pk_bf16_f32 v36, v36, v37
	v_cvt_pk_bf16_f32 v37, v38, v39
	v_cvt_pk_bf16_f32 v38, v32, v33
	v_cvt_pk_bf16_f32 v39, v34, v35
	v_add_u32_e32 v169, 0x24000, v168
	global_store_dwordx4 v169, v[44:47], s[14:15]
	global_store_dwordx4 v169, v[36:39], s[14:15] offset:256
	s_waitcnt lgkmcnt(1)
	v_mul_f32_e32 v28, v166, v28
	v_mul_f32_e32 v29, v166, v29
	v_mul_f32_e32 v30, v166, v30
	v_mul_f32_e32 v31, v166, v31
	v_mul_f32_e32 v24, v166, v24
	v_mul_f32_e32 v25, v166, v25
	v_mul_f32_e32 v26, v166, v26
	v_mul_f32_e32 v27, v166, v27
	v_mul_f32_e32 v20, v166, v20
	v_mul_f32_e32 v21, v166, v21
	v_mul_f32_e32 v22, v166, v22
	v_mul_f32_e32 v23, v166, v23
	v_mul_f32_e32 v16, v166, v16
	v_mul_f32_e32 v17, v166, v17
	v_mul_f32_e32 v18, v166, v18
	v_mul_f32_e32 v19, v166, v19
	v_cvt_pk_bf16_f32 v28, v28, v29
	v_cvt_pk_bf16_f32 v29, v30, v31
	v_cvt_pk_bf16_f32 v30, v24, v25
	v_cvt_pk_bf16_f32 v31, v26, v27
	v_cvt_pk_bf16_f32 v20, v20, v21
	v_cvt_pk_bf16_f32 v21, v22, v23
	v_cvt_pk_bf16_f32 v22, v16, v17
	v_cvt_pk_bf16_f32 v23, v18, v19
	v_add_u32_e32 v169, 0x28000, v168
	global_store_dwordx4 v169, v[28:31], s[14:15]
	global_store_dwordx4 v169, v[20:23], s[14:15] offset:256
	s_waitcnt lgkmcnt(0)
	v_mul_f32_e32 v12, v167, v12
	v_mul_f32_e32 v13, v167, v13
	v_mul_f32_e32 v14, v167, v14
	v_mul_f32_e32 v15, v167, v15
	v_mul_f32_e32 v8, v167, v8
	v_mul_f32_e32 v9, v167, v9
	v_mul_f32_e32 v10, v167, v10
	v_mul_f32_e32 v11, v167, v11
	v_mul_f32_e32 v4, v167, v4
	v_mul_f32_e32 v5, v167, v5
	v_mul_f32_e32 v6, v167, v6
	v_mul_f32_e32 v7, v167, v7
	v_mul_f32_e32 v0, v167, v0
	v_mul_f32_e32 v1, v167, v1
	v_mul_f32_e32 v2, v167, v2
	v_mul_f32_e32 v3, v167, v3
	v_cvt_pk_bf16_f32 v12, v12, v13
	v_cvt_pk_bf16_f32 v13, v14, v15
	v_cvt_pk_bf16_f32 v14, v8, v9
	v_cvt_pk_bf16_f32 v15, v10, v11
	v_cvt_pk_bf16_f32 v4, v4, v5
	v_cvt_pk_bf16_f32 v5, v6, v7
	v_cvt_pk_bf16_f32 v6, v0, v1
	v_cvt_pk_bf16_f32 v7, v2, v3
	v_add_u32_e32 v169, 0x2c000, v168
	global_store_dwordx4 v169, v[12:15], s[14:15]
	global_store_dwordx4 v169, v[4:7], s[14:15] offset:256
	s_andn2_b64 vcc, exec, s[6:7]
	s_mov_b64 s[6:7], -1
	s_cbranch_vccnz .LBB0_803
	s_andn2_b64 vcc, exec, s[12:13]
	s_cbranch_vccnz .LBB0_802
	s_barrier
	s_branch .LBB0_802

; __device__ __forceinline__ unsigned cvtpk(float lo, float hi) { f32x2_t v = {lo, hi}; bf16x2_t b = __builtin_convertvector(v, bf16x2_t); return __builtin_bit_cast(unsigned, b); }
; __device__ __forceinline__ float ssq_sum(const float* p) {
;     const f32x4 a = *(const f32x4*)p, b = *(const f32x4*)(p + 4), c = *(const f32x4*)(p + 8), d = *(const f32x4*)(p + 12);
;     return (((a[0] + a[1]) + (a[2] + a[3])) + ((b[0] + b[1]) + (b[2] + b[3]))) + (((c[0] + c[1]) + (c[2] + c[3])) + ((d[0] + d[1]) + (d[2] + d[3])));
;     __device__ __forceinline__ void operator()(const f32x4 (&acc)[2][2][4][2], const Unit& u, int wr, int wc, int fr, int fq) const {
;         const int row0 = u.pm * BM + wr * 64 + fr, col0 = u.pn * BM + wc * 32 + 8 * fq;
;         float* so = (u.pn == 0) ? ssq_o[0] : (u.pn == 1) ? ssq_o[1] : (u.pn == 2) ? ssq_o[2] : (u.pn == 3) ? ssq_o[3] : nullptr;
; #pragma unroll
;         for (int ai = 0; ai < 2; ++ai)
; #pragma unroll
;             for (int m = 0; m < 4; ++m) {
;                 const int row = row0 + ai * HALF + m * 16; float s = 0.f;
;                 const float rs = ssq_in ? 1.0f / sqrtf(ssq_sum(ssq_in + (size_t)row * 16) * inv_dim + EPS) : 1.0f;
; #pragma unroll
;                 for (int bj = 0; bj < 2; ++bj) {
;                     int col = col0 + bj * HALF; if (hd_in) col = (col / hd_in) * hd_out + (col % hd_in);
;                     const f32x4 v0 = acc[ai][bj][m][0] * rs, v1 = acc[ai][bj][m][1] * rs;
;                     u32x4 w; w.x = cvtpk(v0[0], v0[1]); w.y = cvtpk(v0[2], v0[3]); w.z = cvtpk(v1[0], v1[1]); w.w = cvtpk(v1[2], v1[3]);
;                     *(u32x4*)(O + (size_t)row * ldc + col) = w;
.LBB0_1527:
	v_readlane_b32 vcc_lo, v254, 7
	v_mbcnt_lo_u32_b32 v158, -1, 0
	v_mbcnt_hi_u32_b32 v158, -1, v158
	v_lshrrev_b32_e32 v159, 1, v158
	v_lshl_add_u32 v159, vcc_lo, 5, v159
	v_and_b32_e32 v160, 1, v158
	v_lshl_add_u32 v161, s8, 8, v159
	v_lshlrev_b32_e32 v161, 6, v161
	v_lshl_add_u32 v161, v160, 5, v161
	global_load_dwordx4 v[162:165], v161, s[20:21]
	global_load_dwordx4 v[166:169], v161, s[20:21] offset:16
	v_lshl_add_u32 v170, s8, 8, v150
	v_mul_u32_u24_e32 v170, 0xc00, v170
	v_lshl_or_b32 v171, s9, 8, v152
	v_lshl_add_u32 v170, v171, 1, v170
	v_lshlrev_b32_e32 v159, 2, v159
	v_add_u32_e32 v159, 0x20100, v159
	v_lshlrev_b32_e32 v160, 2, v150
	v_add_u32_e32 v160, 0x20100, v160
	s_waitcnt vmcnt(0)
	v_pk_add_f32 v[162:163], v[162:163], v[164:165]
	v_pk_add_f32 v[166:167], v[166:167], v[168:169]
	v_pk_add_f32 v[162:163], v[162:163], v[166:167]
	v_add_f32_e32 v162, v162, v163
	s_nop 1
	v_add_f32_dpp v162, v162, v162 quad_perm:[1,0,3,2] row_mask:0xf bank_mask:0xf
	v_fmamk_f32 v162, v162, 0x3b000000, v156
	v_rsq_f32_e32 v162, v162
	s_nop 0
	ds_write_b32 v159, v162
	s_waitcnt lgkmcnt(0)
	s_barrier
	ds_read_b32 v162, v160 offset:0
	ds_read_b32 v163, v160 offset:64
	ds_read_b32 v164, v160 offset:128
	ds_read_b32 v165, v160 offset:192
	ds_read_b32 v166, v160 offset:512
	ds_read_b32 v167, v160 offset:576
	ds_read_b32 v168, v160 offset:640
	ds_read_b32 v169, v160 offset:704
	s_waitcnt lgkmcnt(7)
	v_mul_f32_e32 v124, v162, v124
	v_mul_f32_e32 v125, v162, v125
	v_mul_f32_e32 v126, v162, v126
	v_mul_f32_e32 v127, v162, v127
	v_mul_f32_e32 v120, v162, v120
	v_mul_f32_e32 v121, v162, v121
	v_mul_f32_e32 v122, v162, v122
	v_mul_f32_e32 v123, v162, v123
	v_mul_f32_e32 v116, v162, v116
	v_mul_f32_e32 v117, v162, v117
	v_mul_f32_e32 v118, v162, v118
	v_mul_f32_e32 v119, v162, v119
	v_mul_f32_e32 v112, v162, v112
	v_mul_f32_e32 v113, v162, v113
	v_mul_f32_e32 v114, v162, v114
	v_mul_f32_e32 v115, v162, v115
	v_cvt_pk_bf16_f32 v124, v124, v125
	v_cvt_pk_bf16_f32 v125, v126, v127
	v_cvt_pk_bf16_f32 v126, v120, v121
	v_cvt_pk_bf16_f32 v127, v122, v123
	v_cvt_pk_bf16_f32 v116, v116, v117
	v_cvt_pk_bf16_f32 v117, v118, v119
	v_cvt_pk_bf16_f32 v118, v112, v113
	v_cvt_pk_bf16_f32 v119, v114, v115
	global_store_dwordx4 v170, v[124:127], s[16:17]
	global_store_dwordx4 v170, v[116:119], s[16:17] offset:256
	s_waitcnt lgkmcnt(6)
	v_mul_f32_e32 v108, v163, v108
	v_mul_f32_e32 v109, v163, v109
	v_mul_f32_e32 v110, v163, v110
	v_mul_f32_e32 v111, v163, v111
	v_mul_f32_e32 v104, v163, v104
	v_mul_f32_e32 v105, v163, v105
	v_mul_f32_e32 v106, v163, v106
	v_mul_f32_e32 v107, v163, v107
	v_mul_f32_e32 v100, v163, v100
	v_mul_f32_e32 v101, v163, v101
	v_mul_f32_e32 v102, v163, v102
	v_mul_f32_e32 v103, v163, v103
	v_mul_f32_e32 v96, v163, v96
	v_mul_f32_e32 v97, v163, v97
	v_mul_f32_e32 v98, v163, v98
	v_mul_f32_e32 v99, v163, v99
	v_cvt_pk_bf16_f32 v108, v108, v109
	v_cvt_pk_bf16_f32 v109, v110, v111
	v_cvt_pk_bf16_f32 v110, v104, v105
	v_cvt_pk_bf16_f32 v111, v106, v107
	v_cvt_pk_bf16_f32 v100, v100, v101
	v_cvt_pk_bf16_f32 v101, v102, v103
	v_cvt_pk_bf16_f32 v102, v96, v97
	v_cvt_pk_bf16_f32 v103, v98, v99
	v_add_u32_e32 v171, 0xc000, v170
	global_store_dwordx4 v171, v[108:111], s[16:17]
	global_store_dwordx4 v171, v[100:103], s[16:17] offset:256
	s_waitcnt lgkmcnt(5)
	v_mul_f32_e32 v92, v164, v92
	v_mul_f32_e32 v93, v164, v93
	v_mul_f32_e32 v94, v164, v94
	v_mul_f32_e32 v95, v164, v95
	v_mul_f32_e32 v88, v164, v88
	v_mul_f32_e32 v89, v164, v89
	v_mul_f32_e32 v90, v164, v90
	v_mul_f32_e32 v91, v164, v91
	v_mul_f32_e32 v84, v164, v84
	v_mul_f32_e32 v85, v164, v85
	v_mul_f32_e32 v86, v164, v86
	v_mul_f32_e32 v87, v164, v87
	v_mul_f32_e32 v80, v164, v80
	v_mul_f32_e32 v81, v164, v81
	v_mul_f32_e32 v82, v164, v82
	v_mul_f32_e32 v83, v164, v83
	v_cvt_pk_bf16_f32 v92, v92, v93
	v_cvt_pk_bf16_f32 v93, v94, v95
	v_cvt_pk_bf16_f32 v94, v88, v89
	v_cvt_pk_bf16_f32 v95, v90, v91
	v_cvt_pk_bf16_f32 v84, v84, v85
	v_cvt_pk_bf16_f32 v85, v86, v87
	v_cvt_pk_bf16_f32 v86, v80, v81
	v_cvt_pk_bf16_f32 v87, v82, v83
	v_add_u32_e32 v171, 0x18000, v170
	global_store_dwordx4 v171, v[92:95], s[16:17]
	global_store_dwordx4 v171, v[84:87], s[16:17] offset:256
	s_waitcnt lgkmcnt(4)
; __device__ __forceinline__ unsigned cvtpk(float lo, float hi) { f32x2_t v = {lo, hi}; bf16x2_t b = __builtin_convertvector(v, bf16x2_t); return __builtin_bit_cast(unsigned, b); }
;     __device__ __forceinline__ void operator()(const f32x4 (&acc)[2][2][4][2], const Unit& u, int wr, int wc, int fr, int fq) const {
;     ...
;             for (int m = 0; m < 4; ++m) {
;                 const int row = row0 + ai * HALF + m * 16; float s = 0.f;
;                 const float rs = ssq_in ? 1.0f / sqrtf(ssq_sum(ssq_in + (size_t)row * 16) * inv_dim + EPS) : 1.0f;
; #pragma unroll
;                 for (int bj = 0; bj < 2; ++bj) {
;                     int col = col0 + bj * HALF; if (hd_in) col = (col / hd_in) * hd_out + (col % hd_in);
;                     const f32x4 v0 = acc[ai][bj][m][0] * rs, v1 = acc[ai][bj][m][1] * rs;
;                     u32x4 w; w.x = cvtpk(v0[0], v0[1]); w.y = cvtpk(v0[2], v0[3]); w.z = cvtpk(v1[0], v1[1]); w.w = cvtpk(v1[2], v1[3]);
;                     *(u32x4*)(O + (size_t)row * ldc + col) = w;
	v_mul_f32_e32 v76, v165, v76
	v_mul_f32_e32 v77, v165, v77
	v_mul_f32_e32 v78, v165, v78
	v_mul_f32_e32 v79, v165, v79
	v_mul_f32_e32 v72, v165, v72
	v_mul_f32_e32 v73, v165, v73
	v_mul_f32_e32 v74, v165, v74
	v_mul_f32_e32 v75, v165, v75
	v_mul_f32_e32 v68, v165, v68
	v_mul_f32_e32 v69, v165, v69
	v_mul_f32_e32 v70, v165, v70
	v_mul_f32_e32 v71, v165, v71
	v_mul_f32_e32 v64, v165, v64
	v_mul_f32_e32 v65, v165, v65
	v_mul_f32_e32 v66, v165, v66
	v_mul_f32_e32 v67, v165, v67
	v_cvt_pk_bf16_f32 v76, v76, v77
	v_cvt_pk_bf16_f32 v77, v78, v79
	v_cvt_pk_bf16_f32 v78, v72, v73
	v_cvt_pk_bf16_f32 v79, v74, v75
	v_cvt_pk_bf16_f32 v68, v68, v69
	v_cvt_pk_bf16_f32 v69, v70, v71
	v_cvt_pk_bf16_f32 v70, v64, v65
	v_cvt_pk_bf16_f32 v71, v66, v67
	v_add_u32_e32 v171, 0x24000, v170
	global_store_dwordx4 v171, v[76:79], s[16:17]
	global_store_dwordx4 v171, v[68:71], s[16:17] offset:256
	s_waitcnt lgkmcnt(3)
	v_mul_f32_e32 v60, v166, v60
	v_mul_f32_e32 v61, v166, v61
	v_mul_f32_e32 v62, v166, v62
	v_mul_f32_e32 v63, v166, v63
	v_mul_f32_e32 v56, v166, v56
	v_mul_f32_e32 v57, v166, v57
	v_mul_f32_e32 v58, v166, v58
	v_mul_f32_e32 v59, v166, v59
	v_mul_f32_e32 v52, v166, v52
	v_mul_f32_e32 v53, v166, v53
	v_mul_f32_e32 v54, v166, v54
	v_mul_f32_e32 v55, v166, v55
	v_mul_f32_e32 v48, v166, v48
	v_mul_f32_e32 v49, v166, v49
	v_mul_f32_e32 v50, v166, v50
	v_mul_f32_e32 v51, v166, v51
	v_cvt_pk_bf16_f32 v60, v60, v61
	v_cvt_pk_bf16_f32 v61, v62, v63
	v_cvt_pk_bf16_f32 v62, v56, v57
	v_cvt_pk_bf16_f32 v63, v58, v59
	v_cvt_pk_bf16_f32 v52, v52, v53
	v_cvt_pk_bf16_f32 v53, v54, v55
	v_cvt_pk_bf16_f32 v54, v48, v49
	v_cvt_pk_bf16_f32 v55, v50, v51
	v_add_u32_e32 v171, 0x60000, v170
	global_store_dwordx4 v171, v[60:63], s[16:17]
	global_store_dwordx4 v171, v[52:55], s[16:17] offset:256
	s_waitcnt lgkmcnt(2)
	v_mul_f32_e32 v44, v167, v44
	v_mul_f32_e32 v45, v167, v45
	v_mul_f32_e32 v46, v167, v46
	v_mul_f32_e32 v47, v167, v47
	v_mul_f32_e32 v40, v167, v40
	v_mul_f32_e32 v41, v167, v41
	v_mul_f32_e32 v42, v167, v42
	v_mul_f32_e32 v43, v167, v43
	v_mul_f32_e32 v36, v167, v36
	v_mul_f32_e32 v37, v167, v37
	v_mul_f32_e32 v38, v167, v38
	v_mul_f32_e32 v39, v167, v39
	v_mul_f32_e32 v32, v167, v32
	v_mul_f32_e32 v33, v167, v33
	v_mul_f32_e32 v34, v167, v34
	v_mul_f32_e32 v35, v167, v35
	v_cvt_pk_bf16_f32 v44, v44, v45
	v_cvt_pk_bf16_f32 v45, v46, v47
	v_cvt_pk_bf16_f32 v46, v40, v41
	v_cvt_pk_bf16_f32 v47, v42, v43
	v_cvt_pk_bf16_f32 v36, v36, v37
	v_cvt_pk_bf16_f32 v37, v38, v39
	v_cvt_pk_bf16_f32 v38, v32, v33
	v_cvt_pk_bf16_f32 v39, v34, v35
	v_add_u32_e32 v171, 0x6c000, v170
	global_store_dwordx4 v171, v[44:47], s[16:17]
	global_store_dwordx4 v171, v[36:39], s[16:17] offset:256
	s_waitcnt lgkmcnt(1)
	v_mul_f32_e32 v28, v168, v28
	v_mul_f32_e32 v29, v168, v29
	v_mul_f32_e32 v30, v168, v30
	v_mul_f32_e32 v31, v168, v31
	v_mul_f32_e32 v24, v168, v24
	v_mul_f32_e32 v25, v168, v25
	v_mul_f32_e32 v26, v168, v26
	v_mul_f32_e32 v27, v168, v27
	v_mul_f32_e32 v20, v168, v20
	v_mul_f32_e32 v21, v168, v21
	v_mul_f32_e32 v22, v168, v22
	v_mul_f32_e32 v23, v168, v23
	v_mul_f32_e32 v16, v168, v16
	v_mul_f32_e32 v17, v168, v17
	v_mul_f32_e32 v18, v168, v18
	v_mul_f32_e32 v19, v168, v19
	v_cvt_pk_bf16_f32 v28, v28, v29
	v_cvt_pk_bf16_f32 v29, v30, v31
	v_cvt_pk_bf16_f32 v30, v24, v25
	v_cvt_pk_bf16_f32 v31, v26, v27
	v_cvt_pk_bf16_f32 v20, v20, v21
	v_cvt_pk_bf16_f32 v21, v22, v23
	v_cvt_pk_bf16_f32 v22, v16, v17
	v_cvt_pk_bf16_f32 v23, v18, v19
	v_add_u32_e32 v171, 0x78000, v170
	global_store_dwordx4 v171, v[28:31], s[16:17]
	global_store_dwordx4 v171, v[20:23], s[16:17] offset:256
	s_waitcnt lgkmcnt(0)
	v_mul_f32_e32 v12, v169, v12
	v_mul_f32_e32 v13, v169, v13
	v_mul_f32_e32 v14, v169, v14
	v_mul_f32_e32 v15, v169, v15
	v_mul_f32_e32 v8, v169, v8
	v_mul_f32_e32 v9, v169, v9
	v_mul_f32_e32 v10, v169, v10
	v_mul_f32_e32 v11, v169, v11
	v_mul_f32_e32 v4, v169, v4
	v_mul_f32_e32 v5, v169, v5
	v_mul_f32_e32 v6, v169, v6
	v_mul_f32_e32 v7, v169, v7
	v_mul_f32_e32 v0, v169, v0
	v_mul_f32_e32 v1, v169, v1
	v_mul_f32_e32 v2, v169, v2
	v_mul_f32_e32 v3, v169, v3
	v_cvt_pk_bf16_f32 v12, v12, v13
	v_cvt_pk_bf16_f32 v13, v14, v15
	v_cvt_pk_bf16_f32 v14, v8, v9
	v_cvt_pk_bf16_f32 v15, v10, v11
	v_cvt_pk_bf16_f32 v4, v4, v5
	v_cvt_pk_bf16_f32 v5, v6, v7
	v_cvt_pk_bf16_f32 v6, v0, v1
	v_cvt_pk_bf16_f32 v7, v2, v3
	v_add_u32_e32 v171, 0x84000, v170
	global_store_dwordx4 v171, v[12:15], s[16:17]
	global_store_dwordx4 v171, v[4:7], s[16:17] offset:256
	s_andn2_b64 vcc, exec, s[6:7]
	s_mov_b64 s[6:7], -1
	s_cbranch_vccnz .LBB0_1520
	s_andn2_b64 vcc, exec, s[14:15]
	s_cbranch_vccnz .LBB0_1519
	s_barrier
	s_branch .LBB0_1519
